# speedup vs baseline: 1.0367x; 1.0084x over previous
; __global__ void __launch_bounds__(512, 2) mega_kernel(Params p, int ph_begin, int ph_end) {
;     ...
;     int vb = (G & 7) ? (int)blockIdx.x : (((int)blockIdx.x & 7) * (G >> 3) + ((int)blockIdx.x >> 3));
;     ...
;     if (ph > ph_begin && !(G & 7)) {
;       bool uniform = true;
; #pragma unroll
;       for (int j = 0; j < 8; ++j)
;         uniform = uniform && (__hip_atomic_load(p.ctr + 32 + j, __ATOMIC_RELAXED, __HIP_MEMORY_SCOPE_AGENT) == (unsigned)(G >> 3));
;       if (uniform) vb = my_x * (G >> 3) + my_l;
;     }
;     ...
;     vb = __builtin_amdgcn_readfirstlane(vb);
.LBB0_29:
	v_writelane_b32 v254, s14, 58
	s_cmp_le_i32 s14, s18
	v_readlane_b32 s6, v254, 33
	s_cselect_b64 s[2:3], -1, 0
	v_readlane_b32 s7, v254, 34
	s_or_b64 s[2:3], s[6:7], s[2:3]
	s_and_b64 vcc, exec, s[2:3]
	v_readlane_b32 s2, v254, 36
	s_nop 1
	v_mov_b32_e32 v0, s2
	s_cbranch_vccnz .LBB0_38
	v_readlane_b32 s2, v254, 0
	v_readlane_b32 s3, v254, 1
	s_nop 4
	global_load_dword v4, v1, s[2:3] offset:128 sc1
	global_load_dword v5, v1, s[2:3] offset:132 sc1
	global_load_dword v6, v1, s[2:3] offset:136 sc1
	global_load_dword v7, v1, s[2:3] offset:140 sc1
	global_load_dword v8, v1, s[2:3] offset:144 sc1
	global_load_dword v9, v1, s[2:3] offset:148 sc1
	global_load_dword v10, v1, s[2:3] offset:152 sc1
	global_load_dword v11, v1, s[2:3] offset:156 sc1
	v_readlane_b32 s2, v254, 11
	v_readlane_b32 s3, v254, 36
	s_nop 1
	v_mov_b32_e32 v0, s3
	s_waitcnt vmcnt(0)
	s_nop 0
	v_cmp_ne_u32_e32 vcc, s2, v4
	s_cbranch_vccnz .LBB0_38
	v_cmp_ne_u32_e32 vcc, s2, v5
	s_cbranch_vccnz .LBB0_38
	v_cmp_ne_u32_e32 vcc, s2, v6
	s_cbranch_vccnz .LBB0_38
	v_cmp_ne_u32_e32 vcc, s2, v7
	s_cbranch_vccnz .LBB0_38
	v_cmp_ne_u32_e32 vcc, s2, v8
	s_cbranch_vccnz .LBB0_38
	v_cmp_ne_u32_e32 vcc, s2, v9
	s_cbranch_vccnz .LBB0_38
	v_cmp_ne_u32_e32 vcc, s2, v10
	s_cbranch_vccnz .LBB0_38
	v_readlane_b32 s3, v254, 35
	s_nop 1
	v_mov_b32_e32 v2, s3
	v_readlane_b32 s3, v254, 12
	s_nop 1
	v_mov_b32_e32 v3, s3
	v_cmp_eq_u32_e32 vcc, s2, v11
	s_nop 1
	v_cndmask_b32_e32 v0, v2, v3, vcc

; template <int MODE> ...
;     ...
;   const int tid = opaque_tid(), lane = tid & 63, w = tid >> 6;
;   const int g = lane >> 5, ql = lane & 31;
;   const int t_q = qt * 256 + w * 32 + ql;
;   const int w_first = qt * 256 + w * 32, w_last = w_first + 31;
;   const size_t row_q = (size_t)b * LP + t_q;
;   char* Ks = smem;
;   char* Vs = smem + KSZ;
;   int* flags = reinterpret_cast<int*>(smem + MISC_OFF + 64);
;   bf16x8 qf[NKS];
;   {
;     const bf16_t* qsrc = Qg + row_q * QLD + h * QHD + g * 8;
; #pragma unroll
;     for (int ks = 0; ks < NKS; ++ks) qf[ks] = *reinterpret_cast<const bf16x8*>(qsrc + ks * 16);
;   }
;   f32x16 O[4];
; #pragma unroll
;   for (int mb = 0; mb < 4; ++mb)
; #pragma unroll
;     for (int i = 0; i < 16; ++i) O[mb][i] = 0.f;
;   float m_run = -1e30f, l_run = 0.f, carry = 0.f;
;   const int c8 = tid & 7, kr_ = tid >> 3;
;   const int vc = tid & 7, vd = tid >> 3;
;   const bf16_t* k1p = K1g + ((size_t)b * LP + kr_) * 1024 + h * 128 + c8 * 8;
;   const bf16_t* k2p = K2g + ((size_t)b * LP + kr_) * 64 + c8 * 8;
;   const bf16_t* vp0 = VTg + ((size_t)(b * 8 + h) * 128 + vd) * LP + vc * 8;
;   const int ks_off = (c8 * 65 + kr_) * 16;
;   const int vs_off = vd * 136 + vc * 16;
;   uint4 k0, k1, k2, v0, v1;
;   k2 = make_uint4(0u, 0u, 0u, 0u);
;     ...
;   const int kt_hi = (4 * qt + 3 < (L - 1) / 64) ? (4 * qt + 3) : ((L - 1) / 64);
;   LOAD_KV(kt_hi);
;   __syncthreads();
;   STORE_KV(0);
;   LOAD_KV(kt_hi - 1);
;   __syncthreads();
.LBB0_347:
	s_waitcnt vmcnt(2)
	v_mov_b32_e32 v4, v252
	s_ashr_i32 s6, s59, 4
	s_sub_i32 s8, 32, s6
	v_ashrrev_i32_e32 v0, 1, v4
	v_and_b32_e32 v0, 0xffffffe0, v0
	v_and_b32_e32 v43, 31, v4
	v_lshl_add_u32 v166, s8, 8, v0
	s_bfe_u32 s9, s59, 0x10003
	v_or_b32_e32 v30, v166, v43
	s_mul_i32 s74, s9, 0x2010
	v_ashrrev_i32_e32 v31, 31, v30
	v_lshl_add_u64 v[154:155], v[30:31], 0, s[74:75]
	v_mov_b64_e32 v[2:3], s[52:53]
	s_movk_i32 s11, 0xc00
	s_and_b32 s10, s59, 7
	v_mad_u64_u32 v[2:3], s[6:7], v154, s11, v[2:3]
	v_mad_i32_i24 v3, v155, s11, v3
	s_mul_i32 s6, s10, 0x180
	s_mov_b32 s7, s75
	v_lshl_add_u64 v[2:3], v[2:3], 0, s[6:7]
	s_load_dwordx2 s[6:7], s[96:97], 0x118
	v_bfe_u32 v42, v4, 5, 1
	v_ashrrev_i32_e32 v38, 3, v4
	v_lshlrev_b32_e32 v0, 4, v42
	v_ashrrev_i32_e32 v39, 31, v38
	v_lshl_add_u64 v[36:37], v[2:3], 0, v[0:1]
	v_lshl_add_u64 v[2:3], v[38:39], 0, s[74:75]
	v_and_b32_e32 v31, 7, v4
	v_lshlrev_b64 v[4:5], 11, v[2:3]
	v_lshlrev_b64 v[2:3], 7, v[2:3]
	v_lshl_add_u64 v[4:5], s[54:55], 0, v[4:5]
	s_lshl_b32 s12, s10, 7
	s_lshl_b32 s74, s10, 8
	s_waitcnt lgkmcnt(0)
	v_lshl_add_u64 v[2:3], s[6:7], 0, v[2:3]
	s_lshl_b32 s6, s9, 10
	v_lshl_add_u64 v[4:5], v[4:5], 0, s[74:75]
	v_lshlrev_b32_e32 v0, 4, v31
	s_or_b32 s6, s6, s12
	v_lshl_add_u64 v[156:157], v[4:5], 0, v[0:1]
	v_add_u32_e32 v4, s6, v38
	s_load_dwordx2 s[6:7], s[96:97], 0x140
	v_lshl_add_u64 v[158:159], v[2:3], 0, v[0:1]
	v_mul_u32_u24_e32 v31, 0x41, v31
	v_lshlrev_b32_e32 v39, 3, v42
	v_add_lshl_u32 v31, v31, v38, 4
	s_waitcnt lgkmcnt(0)
	v_mov_b64_e32 v[2:3], s[6:7]
	v_mad_i64_i32 v[2:3], s[6:7], v4, s48, v[2:3]
	s_lshl_b32 s6, s8, 2
	s_or_b32 s6, s6, 3
	s_cmp_lt_u32 s8, 32
	s_cselect_b32 s13, s6, 0x80
	s_lshl_b32 s74, s13, 6
	s_lshl_b64 s[6:7], s[74:75], 11
	v_lshl_add_u64 v[160:161], v[2:3], 0, v[0:1]
	v_lshl_add_u64 v[6:7], v[156:157], 0, s[6:7]
	s_lshl_b64 s[6:7], s[74:75], 7
	s_mov_b64 s[8:9], 0x100800
	s_waitcnt vmcnt(0)
	v_lshl_add_u64 v[10:11], v[158:159], 0, s[6:7]
	s_lshl_b64 s[6:7], s[74:75], 1
	v_lshl_add_u64 v[162:163], v[160:161], 0, s[8:9]
	v_lshl_add_u64 v[14:15], v[160:161], 0, s[6:7]
	v_lshl_add_u64 v[18:19], v[162:163], 0, s[6:7]
	global_load_dwordx4 v[2:5], v[6:7], off
	s_nop 0
	global_load_dwordx4 v[6:9], v[6:7], off offset:128
	s_nop 0
	global_load_dwordx4 v[10:13], v[10:11], off
	s_nop 0
	global_load_dwordx4 v[14:17], v[14:15], off
	s_nop 0
	global_load_dwordx4 v[32:35], v[18:19], off
	s_nop 0
	global_load_dwordx4 v[18:21], v[36:37], off
	global_load_dwordx4 v[22:25], v[36:37], off offset:32
	global_load_dwordx4 v[26:29], v[36:37], off offset:64
	global_load_dwordx4 v[96:99], v[36:37], off offset:96
	global_load_dwordx4 v[100:103], v[36:37], off offset:128
	global_load_dwordx4 v[104:107], v[36:37], off offset:160
	global_load_dwordx4 v[108:111], v[36:37], off offset:192
	global_load_dwordx4 v[112:115], v[36:37], off offset:224
	global_load_dwordx4 v[116:119], v[36:37], off offset:256
	global_load_dwordx4 v[120:123], v[36:37], off offset:288
	global_load_dwordx4 v[124:127], v[36:37], off offset:320
	global_load_dwordx4 v[128:131], v[36:37], off offset:352
	s_sub_i32 s6, s74, 64
	s_mov_b32 s7, s75
	s_lshl_b64 s[8:9], s[6:7], 11
	v_lshl_add_u64 v[36:37], v[156:157], 0, s[8:9]
	s_lshl_b64 s[8:9], s[6:7], 7
	s_barrier
; template <int MODE> ...
;     ...
;   LOAD_KV(kt_hi);
;   __syncthreads();
;   STORE_KV(0);
;   LOAD_KV(kt_hi - 1);
;   __syncthreads();
;   int vcur = 0;
;   f32x16 S;
; #pragma unroll
;   for (int i = 0; i < 16; ++i) S[i] = 0.f;
	global_load_dwordx4 v[132:135], v[36:37], off
	global_load_dwordx4 v[136:139], v[36:37], off offset:128
	v_lshl_add_u64 v[36:37], v[158:159], 0, s[8:9]
	s_lshl_b64 s[6:7], s[6:7], 1
	global_load_dwordx4 v[140:143], v[36:37], off
	v_lshl_add_u64 v[36:37], v[160:161], 0, s[6:7]
	v_lshl_add_u64 v[40:41], v[162:163], 0, s[6:7]
	global_load_dwordx4 v[144:147], v[36:37], off
	global_load_dwordx4 v[148:151], v[40:41], off
	s_movk_i32 s8, 0x90
	v_and_b32_e32 v164, 0x60, v0
	v_and_b32_e32 v165, 16, v0
	v_lshrrev_b32_e32 v165, 1, v165
	v_or_b32_e32 v164, v164, v165
	v_mad_u32_u24 v164, v38, s8, v164
	v_add_u32_e32 v0, 0x6180, v164
	v_add_u32_e32 v36, 0x8580, v164
	v_mul_u32_u24_e32 v168, 0x90, v43
	v_lshl_add_u32 v168, v42, 4, v168
	s_movk_i32 s8, 0x41
	v_lshlrev_b32_e32 v165, 2, v42
	s_movk_i32 s6, 0x2010
	v_or_b32_e32 v167, 31, v166
	v_cmp_gt_i32_e64 s[6:7], s6, v166
	s_or_b32 s14, s74, 63
	s_mov_b32 s15, 0
	v_mov_b32_e32 v217, 0xf149f2ca
	v_mov_b32_e32 v216, 0
	s_waitcnt vmcnt(21)
	ds_write_b128 v31, v[2:5]
	s_waitcnt vmcnt(20)
	ds_write_b128 v31, v[6:9] offset:8320
	s_waitcnt vmcnt(19)
	ds_write_b128 v31, v[10:13] offset:16640
	v_xor_b32_e32 v31, 0x10000, v31
	s_waitcnt vmcnt(18)
	ds_write2_b64 v0, v[14:15], v[16:17] offset1:2
	s_waitcnt vmcnt(17)
	ds_write2_b64 v36, v[32:33], v[34:35] offset1:2
	v_mov_b32_e32 v3, 0x82
	v_mov_b32_e32 v4, 0x104
	v_mov_b32_e32 v5, 0x186
	v_mov_b32_e32 v6, 0x208
	v_mov_b32_e32 v7, 0x28a
	v_mov_b32_e32 v8, 0x30c
	v_mov_b32_e32 v9, 0x38e
	v_mov_b32_e32 v10, 0x410
	v_mov_b32_e32 v11, 0x492
	v_mov_b32_e32 v12, 0x514
	v_mov_b32_e32 v13, 0x596
	v_or_b32_e32 v0, 32, v43
	v_mul_u32_u24_e32 v2, 0x41, v42
	v_mad_u32_u24 v3, v42, s8, v3
	v_mad_u32_u24 v4, v42, s8, v4
	v_mad_u32_u24 v5, v42, s8, v5
	v_mad_u32_u24 v6, v42, s8, v6
	v_mad_u32_u24 v7, v42, s8, v7
	v_mad_u32_u24 v8, v42, s8, v8
	v_mad_u32_u24 v9, v42, s8, v9
	v_mad_u32_u24 v10, v42, s8, v10
	v_mad_u32_u24 v11, v42, s8, v11
	v_mad_u32_u24 v12, v42, s8, v12
	v_mad_u32_u24 v13, v42, s8, v13
	v_mov_b32_e32 v14, v1
	v_mov_b32_e32 v15, v1
	v_add_lshl_u32 v169, v2, v0, 4
	v_add_lshl_u32 v170, v3, v0, 4
	v_add_lshl_u32 v171, v4, v0, 4
	v_add_lshl_u32 v172, v5, v0, 4
	v_add_lshl_u32 v173, v6, v0, 4
	v_add_lshl_u32 v174, v7, v0, 4
	v_add_lshl_u32 v175, v8, v0, 4
	v_add_lshl_u32 v176, v9, v0, 4
	v_add_lshl_u32 v177, v10, v0, 4
	v_add_lshl_u32 v178, v11, v0, 4
	v_add_lshl_u32 v179, v12, v0, 4
	v_add_lshl_u32 v203, v13, v0, 4
	v_add_lshl_u32 v204, v2, v43, 4
	v_add_lshl_u32 v205, v3, v43, 4
	v_add_lshl_u32 v206, v4, v43, 4
	v_add_lshl_u32 v207, v5, v43, 4
	v_add_lshl_u32 v208, v6, v43, 4
	v_add_lshl_u32 v209, v7, v43, 4
	v_add_lshl_u32 v210, v8, v43, 4
	v_add_lshl_u32 v211, v9, v43, 4
	v_add_lshl_u32 v212, v10, v43, 4
	v_add_lshl_u32 v213, v11, v43, 4
	v_add_lshl_u32 v214, v12, v43, 4
	v_add_lshl_u32 v215, v13, v43, 4
	v_mov_b32_e32 v0, v1
	v_mov_b32_e32 v2, v1
	v_mov_b32_e32 v3, v1
	v_mov_b32_e32 v4, v1
	v_mov_b32_e32 v5, v1
	v_mov_b32_e32 v6, v1
	v_mov_b32_e32 v7, v1
	v_mov_b32_e32 v8, v1
	v_mov_b32_e32 v9, v1
	v_mov_b32_e32 v10, v1
	v_mov_b32_e32 v11, v1
	v_mov_b32_e32 v12, v1
	v_mov_b32_e32 v13, v1
	v_mov_b64_e32 v[46:47], v[14:15]
	v_mov_b64_e32 v[62:63], v[14:15]
	v_mov_b64_e32 v[78:79], v[14:15]
	v_mov_b64_e32 v[94:95], v[14:15]
	v_mov_b64_e32 v[44:45], v[12:13]
	v_mov_b64_e32 v[42:43], v[10:11]
	v_mov_b64_e32 v[40:41], v[8:9]
	v_mov_b64_e32 v[38:39], v[6:7]
	v_mov_b64_e32 v[36:37], v[4:5]
	v_mov_b64_e32 v[34:35], v[2:3]
	v_mov_b64_e32 v[32:33], v[0:1]
	v_mov_b64_e32 v[60:61], v[12:13]
	v_mov_b64_e32 v[58:59], v[10:11]
	v_mov_b64_e32 v[56:57], v[8:9]
	v_mov_b64_e32 v[54:55], v[6:7]
	v_mov_b64_e32 v[52:53], v[4:5]
	v_mov_b64_e32 v[50:51], v[2:3]
	v_mov_b64_e32 v[48:49], v[0:1]
	v_mov_b64_e32 v[76:77], v[12:13]
	v_mov_b64_e32 v[74:75], v[10:11]
	v_mov_b64_e32 v[72:73], v[8:9]
	v_mov_b64_e32 v[70:71], v[6:7]
	v_mov_b64_e32 v[68:69], v[4:5]
	v_mov_b64_e32 v[66:67], v[2:3]
	v_mov_b64_e32 v[64:65], v[0:1]
	v_mov_b64_e32 v[92:93], v[12:13]
	v_mov_b64_e32 v[90:91], v[10:11]
	v_mov_b64_e32 v[88:89], v[8:9]
	v_mov_b64_e32 v[86:87], v[6:7]
	v_mov_b64_e32 v[84:85], v[4:5]
	v_mov_b64_e32 v[82:83], v[2:3]
	v_mov_b64_e32 v[80:81], v[0:1]
	v_mov_b64_e32 v[16:17], v[14:15]
	v_mov_b64_e32 v[14:15], v[12:13]
	v_mov_b64_e32 v[12:13], v[10:11]
	v_mov_b64_e32 v[10:11], v[8:9]
	v_mov_b64_e32 v[8:9], v[6:7]
	v_mov_b64_e32 v[6:7], v[4:5]
	v_mov_b64_e32 v[4:5], v[2:3]
	v_mov_b64_e32 v[2:3], v[0:1]
	s_waitcnt lgkmcnt(0)
	s_barrier
	s_branch .LBB0_350

; template <int MODE> ...
;     ...
;       if (sub == 0) {
;         __syncthreads();
;         if (has_next) STORE_KV(vcur ^ 1);
;         if (kt > 1) LOAD_KV(kt - 2);
;     ...
;     __syncthreads();
;     vcur ^= 1;
.LBB0_362:
	s_or_b64 exec, exec, s[8:9]
	s_xor_b32 s15, s15, 1
	s_cmp_eq_u32 s13, 0
	s_nop 0
	s_cbranch_scc1 .LBB0_364
	s_mul_i32 s8, s15, 0x4800
	v_add_u32_e32 v0, s8, v164
	v_add_u32_e32 v180, 0x6180, v0
	v_add_u32_e32 v0, 0x8580, v0
	s_waitcnt vmcnt(4)
	ds_write_b128 v31, v[132:135]
	s_waitcnt vmcnt(3)
	ds_write_b128 v31, v[136:139] offset:8320
	s_waitcnt vmcnt(2)
	ds_write_b128 v31, v[140:143] offset:16640
	s_waitcnt vmcnt(1)
	ds_write2_b64 v180, v[144:145], v[146:147] offset1:2
	s_waitcnt vmcnt(0)
	ds_write2_b64 v0, v[148:149], v[150:151] offset1:2
.LBB0_364:
	v_xor_b32_e32 v31, 0x10000, v31
	v_xor_b32_e32 v169, 0x10000, v169
	v_xor_b32_e32 v170, 0x10000, v170
	v_xor_b32_e32 v171, 0x10000, v171
	v_xor_b32_e32 v172, 0x10000, v172
	v_xor_b32_e32 v173, 0x10000, v173
	v_xor_b32_e32 v174, 0x10000, v174
	v_xor_b32_e32 v175, 0x10000, v175
	v_xor_b32_e32 v176, 0x10000, v176
	v_xor_b32_e32 v177, 0x10000, v177
	v_xor_b32_e32 v178, 0x10000, v178
	v_xor_b32_e32 v179, 0x10000, v179
	v_xor_b32_e32 v203, 0x10000, v203
	v_xor_b32_e32 v204, 0x10000, v204
	v_xor_b32_e32 v205, 0x10000, v205
	v_xor_b32_e32 v206, 0x10000, v206
	v_xor_b32_e32 v207, 0x10000, v207
	v_xor_b32_e32 v208, 0x10000, v208
	v_xor_b32_e32 v209, 0x10000, v209
	v_xor_b32_e32 v210, 0x10000, v210
	v_xor_b32_e32 v211, 0x10000, v211
	v_xor_b32_e32 v212, 0x10000, v212
	v_xor_b32_e32 v213, 0x10000, v213
	v_xor_b32_e32 v214, 0x10000, v214
	v_xor_b32_e32 v215, 0x10000, v215
	s_cmp_lt_u32 s13, 2
	s_cbranch_scc1 .LBB0_366
	s_add_i32 s74, s14, 0xffffff41
	s_lshl_b64 s[8:9], s[74:75], 11
	s_waitcnt vmcnt(3)
	v_lshl_add_u64 v[136:137], v[156:157], 0, s[8:9]
	s_lshl_b64 s[8:9], s[74:75], 7
	s_waitcnt vmcnt(2)
	v_lshl_add_u64 v[140:141], v[158:159], 0, s[8:9]
	s_lshl_b64 s[8:9], s[74:75], 1
	s_waitcnt vmcnt(1)
	v_lshl_add_u64 v[144:145], v[160:161], 0, s[8:9]
	s_waitcnt vmcnt(0)
	v_lshl_add_u64 v[148:149], v[162:163], 0, s[8:9]
	global_load_dwordx4 v[132:135], v[136:137], off
	s_nop 0
	global_load_dwordx4 v[136:139], v[136:137], off offset:128
	s_nop 0
	global_load_dwordx4 v[140:143], v[140:141], off
	s_nop 0
	global_load_dwordx4 v[144:147], v[144:145], off
	s_nop 0
	global_load_dwordx4 v[148:151], v[148:149], off
